# dense main loop waves 0-3: fragment-read address arithmetic hoisted in front of the barrier opening the matrix phase; three compiler no-op SALU removed
# baseline (speedup 1.0000x reference)
; #define SBAR() __builtin_amdgcn_sched_barrier(0)
; #define PK4(P, BASE, OUT) do { unsigned a0 = cvtpk(P[BASE + 0], P[BASE + 1]), a1 = cvtpk(P[BASE + 2], P[BASE + 3]);   \
;     unsigned b0 = cvtpk(P[BASE + 4], P[BASE + 5]), b1 = cvtpk(P[BASE + 6], P[BASE + 7]);                              \
;     u32x4 w = {a0, a1, b0, b1}; OUT = *reinterpret_cast<bf16x8*>(&w); } while (0)
; #define KRD(f, d0, kb) asm volatile("ds_read_b128 %0, %2 offset:%3\n\tds_read_b128 %1, %2 offset:%4" : "=&v"(f.a), "=&v"(f.b) : "v"((kb) + koff[(d0) & 3]), "i"(((d0) >> 2) * 128), "i"(((d0) >> 2) * 128 + 8192) : "memory")
; #define LW(n) do { asm volatile("s_waitcnt lgkmcnt(" #n ")" ::: "memory"); SBAR(); } while (0)
; #define PP_BAR(VM) do { if (VM) { asm volatile("s_waitcnt vmcnt(4) lgkmcnt(0)\n\ts_barrier" ::: "memory"); } else { asm volatile("s_waitcnt vmcnt(0) lgkmcnt(0)\n\ts_barrier" ::: "memory"); } } while (0)
; #define PP_BAR_PLAIN() asm volatile("s_waitcnt lgkmcnt(0)\n\ts_barrier" ::: "memory")
; __device__ __forceinline__ void finishSM(f32x16& p0, f32x16& p1, float alpha, float& l_reg, bf16x8& pa0, bf16x8& pa1, bf16x8& pa2, bf16x8& pa3) {
;   for (int r = 0; r < 16; ++r) p1[r] = __builtin_amdgcn_exp2f(p1[r]);
;   float ps = 0; for (int r = 0; r < 16; ++r) ps += p0[r]; for (int r = 0; r < 16; ++r) ps += p1[r];
;   { auto rr = __builtin_amdgcn_permlane32_swap(__float_as_uint(ps), __float_as_uint(ps), false, false);
;     ps = __uint_as_float(rr[0]) + __uint_as_float(rr[1]); }
;   l_reg = l_reg * alpha + ps;
;     ...
;   PK4(p0, 0, pa0); PK4(p0, 8, pa1); PK4(p1, 0, pa2); PK4(p1, 8, pa3);
;     ...
;       if (!(MK_PREB && t + 1 < NT)) { if (!grpB) PP_BAR(t + 2 < NT); else PP_BAR_PLAIN(); }
;       else if (!grpB) PP_BAR(t + 2 < NT);
;       if (!grpB && t + 3 < NT) DMA(t + 3, (t + 3) & 3);
;       SBAR();
;       if (t + 1 < NT) {
;         const int kb_ = kbase0 + ((t + 1) & 3) * (int)SHM_K, vb_ = VBUF(t);
;         KFrag k0_, k1_; VFrag fa_, fb_;
;         KRD(k0_, 0, kb_); KRD(k1_, 1, kb_); pv_rd<0>(fa_, vb_);
;         if (MK_PREB && grpB) asm volatile("s_barrier" ::: "memory");
;     ...
;         LW(10); pA0 = __builtin_amdgcn_mfma_f32_32x32x16_bf16(k0_.a, qr[0], negm, 0, 0, 0); pA1 = __builtin_amdgcn_mfma_f32_32x32x16_bf16(k0_.b, qr[0], negm, 0, 0, 0); SBAR(); KRD(k0_, 2, kb_);
.LBB0_65:
	v_exp_f32_e32 v98, v98
	v_exp_f32_e32 v99, v99
	v_exp_f32_e32 v100, v100
	v_exp_f32_e32 v101, v101
	v_exp_f32_e32 v102, v102
	v_add_f32_e32 v162, 0, v98
	v_exp_f32_e32 v103, v103
	v_add_f32_e32 v162, v99, v162
	v_exp_f32_e32 v104, v104
	v_add_f32_e32 v162, v100, v162
	v_exp_f32_e32 v105, v105
	v_add_f32_e32 v162, v101, v162
	v_exp_f32_e32 v106, v106
	v_add_f32_e32 v162, v102, v162
	v_exp_f32_e32 v107, v107
	v_add_f32_e32 v162, v103, v162
	v_exp_f32_e32 v108, v108
	v_add_f32_e32 v162, v104, v162
	v_exp_f32_e32 v109, v109
	v_add_f32_e32 v162, v105, v162
	v_exp_f32_e32 v110, v110
	v_add_f32_e32 v162, v106, v162
	v_exp_f32_e32 v111, v111
	v_add_f32_e32 v162, v107, v162
	v_exp_f32_e32 v112, v112
	v_add_f32_e32 v162, v108, v162
	v_exp_f32_e32 v113, v113
	v_add_f32_e32 v162, v109, v162
	v_exp_f32_e32 v82, v82
	v_add_f32_e32 v162, v110, v162
	v_exp_f32_e32 v83, v83
	v_add_f32_e32 v162, v111, v162
	v_exp_f32_e32 v84, v84
	v_add_f32_e32 v162, v112, v162
	v_exp_f32_e32 v85, v85
	v_add_f32_e32 v162, v113, v162
	v_exp_f32_e32 v86, v86
	v_add_f32_e32 v162, v82, v162
	v_exp_f32_e32 v87, v87
	v_add_f32_e32 v162, v83, v162
	v_exp_f32_e32 v88, v88
	v_add_f32_e32 v162, v84, v162
	v_exp_f32_e32 v89, v89
	v_add_f32_e32 v162, v85, v162
	v_exp_f32_e32 v90, v90
	v_add_f32_e32 v162, v86, v162
	v_exp_f32_e32 v91, v91
	v_add_f32_e32 v162, v87, v162
	v_exp_f32_e32 v92, v92
	v_add_f32_e32 v162, v88, v162
	v_exp_f32_e32 v93, v93
	v_add_f32_e32 v162, v89, v162
	v_exp_f32_e32 v94, v94
	v_add_f32_e32 v162, v90, v162
	v_exp_f32_e32 v95, v95
	v_add_f32_e32 v162, v91, v162
	v_exp_f32_e32 v96, v96
	v_add_f32_e32 v162, v92, v162
	v_exp_f32_e32 v97, v97
	v_add_f32_e32 v162, v93, v162
	v_add_f32_e32 v162, v94, v162
	v_add_f32_e32 v162, v95, v162
	v_add_f32_e32 v162, v96, v162
	v_add_f32_e32 v243, v97, v162
	v_mov_b32_e32 v245, v243
	v_cvt_pk_bf16_f32 v166, v82, v83
	v_cndmask_b32_e64 v82, 0, 1, s[0:1]
	s_nop 0
	v_permlane32_swap_b32_e32 v243, v245
	v_cmp_ne_u32_e64 s[42:43], 1, v82
	s_andn2_b64 vcc, exec, s[0:1]
	v_cvt_pk_bf16_f32 v174, v98, v99
	v_cvt_pk_bf16_f32 v175, v100, v101
	v_cvt_pk_bf16_f32 v176, v102, v103
	v_cvt_pk_bf16_f32 v177, v104, v105
	v_cvt_pk_bf16_f32 v170, v106, v107
	v_cvt_pk_bf16_f32 v171, v108, v109
	v_cvt_pk_bf16_f32 v172, v110, v111
	v_cvt_pk_bf16_f32 v173, v112, v113
	v_cvt_pk_bf16_f32 v167, v84, v85
	v_cvt_pk_bf16_f32 v168, v86, v87
	v_cvt_pk_bf16_f32 v169, v88, v89
	v_cvt_pk_bf16_f32 v162, v90, v91
	v_cvt_pk_bf16_f32 v163, v92, v93
	v_cvt_pk_bf16_f32 v164, v94, v95
	v_cvt_pk_bf16_f32 v165, v96, v97
	s_cbranch_vccnz .LBB0_67
	s_add_i32 vcc_hi, s86, 0xc000
	s_and_b32 vcc_hi, vcc_hi, 0xc000
	s_add_i32 vcc_lo, s13, vcc_hi
	s_add_i32 vcc_hi, s14, vcc_hi
	s_add_u32 s84, s86, 0x4000
	s_addc_u32 s85, s87, 0
	s_and_b32 s87, s84, 0xc000
	s_and_b32 s15, s86, 0xc000
	v_add_u32_e32 v248, s87, v239
	v_add_u32_e32 v247, s87, v238
	v_add_u32_e32 v246, s15, v244
	s_waitcnt vmcnt(4) lgkmcnt(0)
	s_barrier
	s_mov_b32 m0, vcc_lo
	s_nop 0
	global_load_lds_dwordx4 v[182:183], off
	s_mov_b32 m0, vcc_hi
	s_nop 0
	global_load_lds_dwordx4 v[184:185], off
	s_add_i32 m0, vcc_lo, 0x400
	s_nop 0
	global_load_lds_dwordx4 v[178:179], off
	s_add_i32 m0, vcc_hi, 0x400
	s_nop 0
	global_load_lds_dwordx4 v[180:181], off
	s_branch .Ldense_mreads
.LBB0_67:
	s_add_u32 s84, s86, 0x4000
	s_addc_u32 s85, s87, 0
	s_and_b32 s87, s84, 0xc000
	s_and_b32 s15, s86, 0xc000
	v_add_u32_e32 v248, s87, v239
	v_add_u32_e32 v247, s87, v238
	v_add_u32_e32 v246, s15, v244
.Ldense_mreads:
	ds_read_b128 v[82:85], v248 offset:0
	ds_read_b128 v[202:205], v248 offset:0x2000
	ds_read_b128 v[198:201], v247 offset:0
	ds_read_b128 v[194:197], v247 offset:0x2000
	ds_read_b64_tr_b16 v[190:191], v246 offset:0
	ds_read_b64_tr_b16 v[192:193], v246 offset:0x800
	ds_read_b64_tr_b16 v[186:187], v246 offset:0x1000
	ds_read_b64_tr_b16 v[188:189], v246 offset:0x1800
	ds_read_b64_tr_b16 v[182:183], v246 offset:0x2000
	ds_read_b64_tr_b16 v[184:185], v246 offset:0x2800
	ds_read_b64_tr_b16 v[178:179], v246 offset:0x3000
	ds_read_b64_tr_b16 v[180:181], v246 offset:0x3800
	s_and_b64 vcc, exec, s[44:45]
	s_cbranch_vccnz .LBB0_69
	s_barrier
